# NSA top-16 selection via exact radix select (31 ballot steps + mbcnt tie prefix) instead of 64-step readlane rank loop
# speedup vs baseline: 1.1211x; 1.0206x over previous
.LBB0_675:
	v_add_u32_e32 v37, s30, v34
	v_add_u32_e32 v0, s45, v37
	v_ashrrev_i32_e32 v38, 6, v0
	v_cmp_eq_u32_e64 s[0:1], v62, v38
	v_add_u32_e32 v38, -1, v38
	s_or_b64 s[38:39], vcc, s[0:1]
	v_cmp_eq_u32_e64 s[0:1], v62, v38
	s_or_b64 s[0:1], s[38:39], s[0:1]
	v_cmp_le_i32_e64 s[38:39], v35, v0
	v_mul_lo_u32 v0, v37, s25
	v_add_u32_e32 v38, v36, v0
	v_add_u32_e32 v0, 0, v0
	v_lshl_add_u32 v39, v62, 2, v0
	ds_read_b32 v38, v38
	ds_read_b32 v40, v39 offset:8320
	s_mov_b32 s46, 0
	s_waitcnt lgkmcnt(0)
	v_add_f32_e32 v38, v38, v40
	ds_read_b32 v40, v39 offset:16640
	ds_read_b32 v39, v39 offset:24960
	s_waitcnt lgkmcnt(1)
	v_add_f32_e32 v38, v38, v40
	s_waitcnt lgkmcnt(0)
	v_add_f32_e32 v38, v38, v39
	v_cndmask_b32_e64 v38, v212, v38, s[38:39]
	v_cndmask_b32_e64 v38, v38, v215, s[0:1]
	v_add_u32_e32 v39, 1, v38
	v_cndmask_b32_e64 v39, 0, v39, s[38:39]
	s_mov_b32 s46, 0
	s_or_b32 s101, s46, 0x40000000
	v_cmp_le_u32_e64 s[40:41], s101, v39
	s_bcnt1_i32_b64 s42, s[40:41]
	s_cmp_ge_u32 s42, 16
	s_cselect_b32 s46, s101, s46
	s_or_b32 s101, s46, 0x20000000
	v_cmp_le_u32_e64 s[40:41], s101, v39
	s_bcnt1_i32_b64 s42, s[40:41]
	s_cmp_ge_u32 s42, 16
	s_cselect_b32 s46, s101, s46
	s_or_b32 s101, s46, 0x10000000
	v_cmp_le_u32_e64 s[40:41], s101, v39
	s_bcnt1_i32_b64 s42, s[40:41]
	s_cmp_ge_u32 s42, 16
	s_cselect_b32 s46, s101, s46
	s_or_b32 s101, s46, 0x8000000
	v_cmp_le_u32_e64 s[40:41], s101, v39
	s_bcnt1_i32_b64 s42, s[40:41]
	s_cmp_ge_u32 s42, 16
	s_cselect_b32 s46, s101, s46
	s_or_b32 s101, s46, 0x4000000
	v_cmp_le_u32_e64 s[40:41], s101, v39
	s_bcnt1_i32_b64 s42, s[40:41]
	s_cmp_ge_u32 s42, 16
	s_cselect_b32 s46, s101, s46
	s_or_b32 s101, s46, 0x2000000
	v_cmp_le_u32_e64 s[40:41], s101, v39
	s_bcnt1_i32_b64 s42, s[40:41]
	s_cmp_ge_u32 s42, 16
	s_cselect_b32 s46, s101, s46
	s_or_b32 s101, s46, 0x1000000
	v_cmp_le_u32_e64 s[40:41], s101, v39
	s_bcnt1_i32_b64 s42, s[40:41]
	s_cmp_ge_u32 s42, 16
	s_cselect_b32 s46, s101, s46
	s_or_b32 s101, s46, 0x800000
	v_cmp_le_u32_e64 s[40:41], s101, v39
	s_bcnt1_i32_b64 s42, s[40:41]
	s_cmp_ge_u32 s42, 16
	s_cselect_b32 s46, s101, s46
	s_or_b32 s101, s46, 0x400000
	v_cmp_le_u32_e64 s[40:41], s101, v39
	s_bcnt1_i32_b64 s42, s[40:41]
	s_cmp_ge_u32 s42, 16
	s_cselect_b32 s46, s101, s46
	s_or_b32 s101, s46, 0x200000
	v_cmp_le_u32_e64 s[40:41], s101, v39
	s_bcnt1_i32_b64 s42, s[40:41]
	s_cmp_ge_u32 s42, 16
	s_cselect_b32 s46, s101, s46
	s_or_b32 s101, s46, 0x100000
	v_cmp_le_u32_e64 s[40:41], s101, v39
	s_bcnt1_i32_b64 s42, s[40:41]
	s_cmp_ge_u32 s42, 16
	s_cselect_b32 s46, s101, s46
	s_or_b32 s101, s46, 0x80000
	v_cmp_le_u32_e64 s[40:41], s101, v39
	s_bcnt1_i32_b64 s42, s[40:41]
	s_cmp_ge_u32 s42, 16
	s_cselect_b32 s46, s101, s46
	s_or_b32 s101, s46, 0x40000
	v_cmp_le_u32_e64 s[40:41], s101, v39
	s_bcnt1_i32_b64 s42, s[40:41]
	s_cmp_ge_u32 s42, 16
	s_cselect_b32 s46, s101, s46
	s_or_b32 s101, s46, 0x20000
	v_cmp_le_u32_e64 s[40:41], s101, v39
	s_bcnt1_i32_b64 s42, s[40:41]
	s_cmp_ge_u32 s42, 16
	s_cselect_b32 s46, s101, s46
	s_or_b32 s101, s46, 0x10000
	v_cmp_le_u32_e64 s[40:41], s101, v39
	s_bcnt1_i32_b64 s42, s[40:41]
	s_cmp_ge_u32 s42, 16
	s_cselect_b32 s46, s101, s46
	s_or_b32 s101, s46, 0x8000
	v_cmp_le_u32_e64 s[40:41], s101, v39
	s_bcnt1_i32_b64 s42, s[40:41]
	s_cmp_ge_u32 s42, 16
	s_cselect_b32 s46, s101, s46
	s_or_b32 s101, s46, 0x4000
	v_cmp_le_u32_e64 s[40:41], s101, v39
	s_bcnt1_i32_b64 s42, s[40:41]
	s_cmp_ge_u32 s42, 16
	s_cselect_b32 s46, s101, s46
	s_or_b32 s101, s46, 0x2000
	v_cmp_le_u32_e64 s[40:41], s101, v39
	s_bcnt1_i32_b64 s42, s[40:41]
	s_cmp_ge_u32 s42, 16
	s_cselect_b32 s46, s101, s46
	s_or_b32 s101, s46, 0x1000
	v_cmp_le_u32_e64 s[40:41], s101, v39
	s_bcnt1_i32_b64 s42, s[40:41]
	s_cmp_ge_u32 s42, 16
	s_cselect_b32 s46, s101, s46
	s_or_b32 s101, s46, 0x800
	v_cmp_le_u32_e64 s[40:41], s101, v39
	s_bcnt1_i32_b64 s42, s[40:41]
	s_cmp_ge_u32 s42, 16
	s_cselect_b32 s46, s101, s46
	s_or_b32 s101, s46, 0x400
	v_cmp_le_u32_e64 s[40:41], s101, v39
	s_bcnt1_i32_b64 s42, s[40:41]
	s_cmp_ge_u32 s42, 16
	s_cselect_b32 s46, s101, s46
	s_or_b32 s101, s46, 0x200
	v_cmp_le_u32_e64 s[40:41], s101, v39
	s_bcnt1_i32_b64 s42, s[40:41]
	s_cmp_ge_u32 s42, 16
	s_cselect_b32 s46, s101, s46
	s_or_b32 s101, s46, 0x100
	v_cmp_le_u32_e64 s[40:41], s101, v39
	s_bcnt1_i32_b64 s42, s[40:41]
	s_cmp_ge_u32 s42, 16
	s_cselect_b32 s46, s101, s46
	s_or_b32 s101, s46, 0x80
	v_cmp_le_u32_e64 s[40:41], s101, v39
	s_bcnt1_i32_b64 s42, s[40:41]
	s_cmp_ge_u32 s42, 16
	s_cselect_b32 s46, s101, s46
	s_or_b32 s101, s46, 0x40
	v_cmp_le_u32_e64 s[40:41], s101, v39
	s_bcnt1_i32_b64 s42, s[40:41]
	s_cmp_ge_u32 s42, 16
	s_cselect_b32 s46, s101, s46
	s_or_b32 s101, s46, 0x20
	v_cmp_le_u32_e64 s[40:41], s101, v39
	s_bcnt1_i32_b64 s42, s[40:41]
	s_cmp_ge_u32 s42, 16
	s_cselect_b32 s46, s101, s46
	s_or_b32 s101, s46, 0x10
	v_cmp_le_u32_e64 s[40:41], s101, v39
	s_bcnt1_i32_b64 s42, s[40:41]
	s_cmp_ge_u32 s42, 16
	s_cselect_b32 s46, s101, s46
	s_or_b32 s101, s46, 0x8
	v_cmp_le_u32_e64 s[40:41], s101, v39
	s_bcnt1_i32_b64 s42, s[40:41]
	s_cmp_ge_u32 s42, 16
	s_cselect_b32 s46, s101, s46
	s_or_b32 s101, s46, 0x4
	v_cmp_le_u32_e64 s[40:41], s101, v39
	s_bcnt1_i32_b64 s42, s[40:41]
	s_cmp_ge_u32 s42, 16
	s_cselect_b32 s46, s101, s46
	s_or_b32 s101, s46, 0x2
	v_cmp_le_u32_e64 s[40:41], s101, v39
	s_bcnt1_i32_b64 s42, s[40:41]
	s_cmp_ge_u32 s42, 16
	s_cselect_b32 s46, s101, s46
	s_or_b32 s101, s46, 0x1
	v_cmp_le_u32_e64 s[40:41], s101, v39
	s_bcnt1_i32_b64 s42, s[40:41]
	s_cmp_ge_u32 s42, 16
	s_cselect_b32 s46, s101, s46
	v_cmp_lt_u32_e64 s[40:41], s46, v39
	v_cmp_eq_u32_e64 s[42:43], s46, v39
	s_bcnt1_i32_b64 s100, s[40:41]
	s_sub_u32 s100, 16, s100
	v_mbcnt_lo_u32_b32 v40, s42, 0
	v_mbcnt_hi_u32_b32 v40, s43, v40
	v_cmp_gt_u32_e64 s[0:1], s100, v40
	s_and_b64 s[0:1], s[0:1], s[42:43]
	s_or_b64 s[0:1], s[0:1], s[40:41]
	s_and_b64 s[0:1], s[0:1], s[38:39]
	s_nop 0
	v_cndmask_b32_e64 v38, 0, 1, s[0:1]
	v_cmp_ne_u32_e64 s[38:39], 0, v38
	s_and_saveexec_b64 s[0:1], vcc
	s_cbranch_execz .LBB0_674
	s_movk_i32 s40, 0xff04
	v_mad_u64_u32 v[38:39], s[40:41], v37, s40, v[0:1]
	v_mov_b64_e32 v[40:41], s[38:39]
	ds_write_b64 v38, v[40:41] offset:33280
	s_branch .LBB0_674
